# input-only f32->bf16 conversion of pool rows (PB) moved from P3 to CUs 8..255 after they finish P6 (P6 tail shadow); P3 skips it
# speedup vs baseline: 1.0031x; 1.0031x over previous
.LBB0_694:
	s_or_b64 exec, exec, s[12:13]
	s_mov_b32 s100, s74
	v_readlane_b32 s101, v255, 0
	s_cmpk_lg_i32 s93, 0x100
	s_cbranch_scc1 .Lconv_entry
	s_mov_b64 s[38:39], 0
.Lconv_entry:
	v_mov_b32_e32 v20, v228
	s_mov_b32 s12, s100
	s_ashr_i32 s13, s12, 31
	s_mov_b32 s18, s101
	s_lshl_b64 s[0:1], s[12:13], 9
	v_ashrrev_i32_e32 v21, 31, v20
	v_readlane_b32 s19, v255, 1
	v_lshl_add_u64 v[18:19], s[0:1], 0, v[20:21]
	s_ashr_i32 s19, s18, 31
	s_lshl_b64 s[10:11], s[18:19], 9
	v_cmp_gt_u64_e32 vcc, s[38:39], v[18:19]
	s_mul_hi_i32 s21, s18, 0x600
	s_mul_i32 s20, s18, 0x600
	s_mul_i32 s36, s18, 0x1800
	s_and_saveexec_b64 s[22:23], vcc
	s_cbranch_execz .LBB0_719
	v_readlane_b32 s0, v255, 49
	s_add_u32 s24, s76, 0x32aba000
	v_readlane_b32 s1, v255, 50
	v_readlane_b32 s4, v255, 32
	s_addc_u32 s25, s77, 0
	s_lshl_b64 s[0:1], s[0:1], 26
	v_readlane_b32 s6, v255, 34
	v_readlane_b32 s7, v255, 35
	s_add_u32 s26, s6, s0
	s_addc_u32 s27, s7, s1
	v_readlane_b32 s0, v255, 6
	v_readlane_b32 s1, v255, 7
	s_add_u32 s28, s0, s58
	s_addc_u32 s29, s1, s59
	s_lshl_b64 s[0:1], s[12:13], 13
	v_lshl_add_u64 v[22:23], v[20:21], 4, s[0:1]
	s_lshl_b64 s[0:1], s[12:13], 11
	s_lshl_b64 s[30:31], s[18:19], 10
	s_lshl_b64 s[34:35], s[18:19], 14
	s_lshl_b64 s[40:41], s[18:19], 15
	s_lshl_b64 s[42:43], s[18:19], 12
	v_lshl_add_u64 v[24:25], v[20:21], 2, s[0:1]
	s_lshl_b64 s[44:45], s[18:19], 13
	s_lshl_b64 s[46:47], s[18:19], 11
	s_mov_b64 s[48:49], 0
	v_mov_b64_e32 v[14:15], v[18:19]
	v_readlane_b32 s5, v255, 33
	s_branch .LBB0_697

.LBB0_719:
	s_or_b64 exec, exec, s[22:23]
	s_cmpk_lg_i32 s101, 0xf8
	s_cbranch_scc1 .Lconv_cont
	s_cmpk_lg_i32 s93, 0x100
	s_cbranch_scc1 .Lconv_cont
	s_movk_i32 s101, 0
	s_branch .Lp6_xbar
.Lconv_cont:
	s_mov_b64 s[0:1], 0x100000
	v_cmp_gt_u64_e32 vcc, s[0:1], v[18:19]
	s_and_saveexec_b64 s[22:23], vcc
	v_readlane_b32 s38, v255, 49
	v_readlane_b32 s39, v255, 50
	s_cbranch_execz .LBB0_732
	v_readlane_b32 s24, v255, 10
	v_readlane_b32 s28, v255, 14
	v_readlane_b32 s29, v255, 15
	s_lshl_b64 s[0:1], s[38:39], 24
	v_readlane_b32 s30, v255, 16
	v_readlane_b32 s31, v255, 17
	s_mov_b64 s[4:5], s[28:29]
	v_readlane_b32 s25, v255, 11
	s_add_u32 s24, s4, s0
	v_readlane_b32 s26, v255, 12
	v_readlane_b32 s27, v255, 13
	s_addc_u32 s25, s5, s1
	s_lshl_b64 s[0:1], s[12:13], 11
	s_mov_b64 s[6:7], s[30:31]
	s_lshl_b64 s[26:27], s[18:19], 10
	s_lshl_b64 s[28:29], s[18:19], 12
	v_lshl_add_u64 v[22:23], v[20:21], 2, s[0:1]
	s_lshl_b64 s[30:31], s[18:19], 13
	s_lshl_b64 s[34:35], s[18:19], 11
	s_mov_b64 s[40:41], 0
	v_mov_b64_e32 v[26:27], v[18:19]
	s_branch .LBB0_722

.LBB0_1342:
	s_cmpk_lg_i32 s93, 0x100
	s_cbranch_scc1 .Lp6_xbar
	s_cmp_lt_u32 s62, 8
	s_cbranch_scc1 .Lp6_xbar
	s_sub_i32 s100, s62, 8
	s_movk_i32 s101, 0xf8
	s_mov_b64 s[38:39], 0x408000
	v_readlane_b32 s58, v255, 49
	v_readlane_b32 s59, v255, 50
	s_nop 0
	s_lshl_b64 s[58:59], s[58:59], 19
	s_branch .Lconv_entry
